# QKV epilogue V^T path: 4x4 key-by-dim transpose inside lane quads (DPP), one 8-byte store per accumulator quad instead of four 2-byte stores
# speedup vs baseline: 1.0012x; 1.0012x over previous
.LBB0_714:
	s_lshl_b32 s16, s48, 5
	s_add_i32 s16, s16, s31
	s_or_b32 s16, s16, s29
	s_ashr_i32 s17, s16, 31
	s_lshl_b64 s[16:17], s[16:17], 16
	s_add_u32 s96, s33, s16
	s_addc_u32 s97, s30, s17
	v_mov_b32_e32 v145, v149
	v_lshl_or_b32 v130, s29, 6, v172
	v_lshl_add_u64 v[128:129], s[96:97], 0, v[144:145]
	v_mov_b32_e32 v181, v149
	v_lshl_add_u64 v[136:137], v[128:129], 0, v[180:181]
	v_mul_u32_u24_e32 v128, 0x9000, v130
	v_lshlrev_b32_e32 v148, 1, v128
	v_lshl_add_u64 v[134:135], s[24:25], 0, v[148:149]
	v_lshl_add_u64 v[128:129], v[182:183], 1, v[134:135]
	v_mbcnt_lo_u32_b32 v197, -1, 0
	v_mbcnt_hi_u32_b32 v197, -1, v197
	v_and_b32_e32 v197, 3, v197
	v_mul_u32_u24_e32 v148, 0x11ffe, v197
	v_lshl_add_u64 v[132:133], v[148:149], 0, v[128:129]
	s_mov_b32 s40, 0xaaaaaaaa
	s_mov_b32 s41, 0xaaaaaaaa
	s_mov_b32 vcc_lo, 0xcccccccc
	s_mov_b32 vcc_hi, 0xcccccccc
	s_mov_b64 s[16:17], 0x0
	v_lshl_add_u64 v[142:143], v[136:137], 0, s[16:17]
	s_andn2_b64 s[16:17], exec, s[56:57]
	s_cmp_lg_u64 s[16:17], 0
	s_cbranch_scc1 .Lvt_noctx0
	global_store_dwordx4 v[142:143], v[124:127], off
	global_store_dwordx4 v[142:143], v[120:123], off offset:16
	global_store_dwordx4 v[142:143], v[116:119], off offset:128
	global_store_dwordx4 v[142:143], v[112:115], off offset:144
	s_nop 1
.Lvt_noctx0:
	v_cndmask_b32_e64 v131, v125, v124, s[40:41]
	v_cndmask_b32_e64 v186, v127, v126, s[40:41]
	v_cndmask_b32_e64 v187, v121, v120, s[40:41]
	v_cndmask_b32_e64 v192, v123, v122, s[40:41]
	v_mov_b32_dpp v193, v131 quad_perm:[1,0,3,2] row_mask:0xf bank_mask:0xf
	v_mov_b32_dpp v194, v186 quad_perm:[1,0,3,2] row_mask:0xf bank_mask:0xf
	v_mov_b32_dpp v195, v187 quad_perm:[1,0,3,2] row_mask:0xf bank_mask:0xf
	v_mov_b32_dpp v196, v192 quad_perm:[1,0,3,2] row_mask:0xf bank_mask:0xf
	v_cndmask_b32_e64 v124, v124, v193, s[40:41]
	v_cndmask_b32_e64 v125, v193, v125, s[40:41]
	v_cndmask_b32_e64 v126, v126, v194, s[40:41]
	v_cndmask_b32_e64 v127, v194, v127, s[40:41]
	v_cndmask_b32_e64 v120, v120, v195, s[40:41]
	v_cndmask_b32_e64 v121, v195, v121, s[40:41]
	v_cndmask_b32_e64 v122, v122, v196, s[40:41]
	v_cndmask_b32_e64 v123, v196, v123, s[40:41]
	v_cndmask_b32_e64 v131, v126, v124, vcc
	v_cndmask_b32_e64 v186, v127, v125, vcc
	v_cndmask_b32_e64 v187, v122, v120, vcc
	v_cndmask_b32_e64 v192, v123, v121, vcc
	v_mov_b32_dpp v193, v131 quad_perm:[2,3,0,1] row_mask:0xf bank_mask:0xf
	v_mov_b32_dpp v194, v186 quad_perm:[2,3,0,1] row_mask:0xf bank_mask:0xf
	v_mov_b32_dpp v195, v187 quad_perm:[2,3,0,1] row_mask:0xf bank_mask:0xf
	v_mov_b32_dpp v196, v192 quad_perm:[2,3,0,1] row_mask:0xf bank_mask:0xf
	v_cndmask_b32_e64 v124, v124, v193, vcc
	v_cndmask_b32_e64 v126, v193, v126, vcc
	v_cndmask_b32_e64 v125, v125, v194, vcc
	v_cndmask_b32_e64 v127, v194, v127, vcc
	v_cndmask_b32_e64 v120, v120, v195, vcc
	v_cndmask_b32_e64 v122, v195, v122, vcc
	v_cndmask_b32_e64 v121, v121, v196, vcc
	v_cndmask_b32_e64 v123, v196, v123, vcc
	v_cvt_pk_bf16_f32 v146, v124, v125
	v_cvt_pk_bf16_f32 v147, v126, v127
	s_mov_b64 s[16:17], 0x0
	v_lshl_add_u64 v[138:139], v[132:133], 0, s[16:17]
	global_store_dwordx2 v[138:139], v[146:147], off
	v_cvt_pk_bf16_f32 v184, v120, v121
	v_cvt_pk_bf16_f32 v185, v122, v123
	s_mov_b64 s[16:17], 0x48000
	v_lshl_add_u64 v[140:141], v[132:133], 0, s[16:17]
	global_store_dwordx2 v[140:141], v[184:185], off
	v_cndmask_b32_e64 v131, v117, v116, s[40:41]
	v_cndmask_b32_e64 v186, v119, v118, s[40:41]
	v_cndmask_b32_e64 v187, v113, v112, s[40:41]
	v_cndmask_b32_e64 v192, v115, v114, s[40:41]
	v_mov_b32_dpp v193, v131 quad_perm:[1,0,3,2] row_mask:0xf bank_mask:0xf
	v_mov_b32_dpp v194, v186 quad_perm:[1,0,3,2] row_mask:0xf bank_mask:0xf
	v_mov_b32_dpp v195, v187 quad_perm:[1,0,3,2] row_mask:0xf bank_mask:0xf
	v_mov_b32_dpp v196, v192 quad_perm:[1,0,3,2] row_mask:0xf bank_mask:0xf
	v_cndmask_b32_e64 v116, v116, v193, s[40:41]
	v_cndmask_b32_e64 v117, v193, v117, s[40:41]
	v_cndmask_b32_e64 v118, v118, v194, s[40:41]
	v_cndmask_b32_e64 v119, v194, v119, s[40:41]
	v_cndmask_b32_e64 v112, v112, v195, s[40:41]
	v_cndmask_b32_e64 v113, v195, v113, s[40:41]
	v_cndmask_b32_e64 v114, v114, v196, s[40:41]
	v_cndmask_b32_e64 v115, v196, v115, s[40:41]
	v_cndmask_b32_e64 v131, v118, v116, vcc
	v_cndmask_b32_e64 v186, v119, v117, vcc
	v_cndmask_b32_e64 v187, v114, v112, vcc
	v_cndmask_b32_e64 v192, v115, v113, vcc
	v_mov_b32_dpp v193, v131 quad_perm:[2,3,0,1] row_mask:0xf bank_mask:0xf
	v_mov_b32_dpp v194, v186 quad_perm:[2,3,0,1] row_mask:0xf bank_mask:0xf
	v_mov_b32_dpp v195, v187 quad_perm:[2,3,0,1] row_mask:0xf bank_mask:0xf
	v_mov_b32_dpp v196, v192 quad_perm:[2,3,0,1] row_mask:0xf bank_mask:0xf
	v_cndmask_b32_e64 v116, v116, v193, vcc
	v_cndmask_b32_e64 v118, v193, v118, vcc
	v_cndmask_b32_e64 v117, v117, v194, vcc
	v_cndmask_b32_e64 v119, v194, v119, vcc
	v_cndmask_b32_e64 v112, v112, v195, vcc
	v_cndmask_b32_e64 v114, v195, v114, vcc
	v_cndmask_b32_e64 v113, v113, v196, vcc
	v_cndmask_b32_e64 v115, v196, v115, vcc
	v_cvt_pk_bf16_f32 v146, v116, v117
	v_cvt_pk_bf16_f32 v147, v118, v119
	s_mov_b64 s[16:17], 0x240000
	v_lshl_add_u64 v[138:139], v[132:133], 0, s[16:17]
	global_store_dwordx2 v[138:139], v[146:147], off
	v_cvt_pk_bf16_f32 v184, v112, v113
	v_cvt_pk_bf16_f32 v185, v114, v115
	s_mov_b64 s[16:17], 0x288000
	v_lshl_add_u64 v[140:141], v[132:133], 0, s[16:17]
	global_store_dwordx2 v[140:141], v[184:185], off
	s_mov_b64 s[16:17], 0x1000
	v_lshl_add_u64 v[142:143], v[136:137], 0, s[16:17]
	s_andn2_b64 s[16:17], exec, s[56:57]
	s_cmp_lg_u64 s[16:17], 0
	s_cbranch_scc1 .Lvt_noctx1
	global_store_dwordx4 v[142:143], v[108:111], off
	global_store_dwordx4 v[142:143], v[104:107], off offset:16
	global_store_dwordx4 v[142:143], v[100:103], off offset:128
	global_store_dwordx4 v[142:143], v[96:99], off offset:144
	s_nop 1
.Lvt_noctx1:
	v_cndmask_b32_e64 v131, v109, v108, s[40:41]
	v_cndmask_b32_e64 v186, v111, v110, s[40:41]
	v_cndmask_b32_e64 v187, v105, v104, s[40:41]
	v_cndmask_b32_e64 v192, v107, v106, s[40:41]
	v_mov_b32_dpp v193, v131 quad_perm:[1,0,3,2] row_mask:0xf bank_mask:0xf
	v_mov_b32_dpp v194, v186 quad_perm:[1,0,3,2] row_mask:0xf bank_mask:0xf
	v_mov_b32_dpp v195, v187 quad_perm:[1,0,3,2] row_mask:0xf bank_mask:0xf
	v_mov_b32_dpp v196, v192 quad_perm:[1,0,3,2] row_mask:0xf bank_mask:0xf
	v_cndmask_b32_e64 v108, v108, v193, s[40:41]
	v_cndmask_b32_e64 v109, v193, v109, s[40:41]
	v_cndmask_b32_e64 v110, v110, v194, s[40:41]
	v_cndmask_b32_e64 v111, v194, v111, s[40:41]
	v_cndmask_b32_e64 v104, v104, v195, s[40:41]
	v_cndmask_b32_e64 v105, v195, v105, s[40:41]
	v_cndmask_b32_e64 v106, v106, v196, s[40:41]
	v_cndmask_b32_e64 v107, v196, v107, s[40:41]
	v_cndmask_b32_e64 v131, v110, v108, vcc
	v_cndmask_b32_e64 v186, v111, v109, vcc
	v_cndmask_b32_e64 v187, v106, v104, vcc
	v_cndmask_b32_e64 v192, v107, v105, vcc
	v_mov_b32_dpp v193, v131 quad_perm:[2,3,0,1] row_mask:0xf bank_mask:0xf
	v_mov_b32_dpp v194, v186 quad_perm:[2,3,0,1] row_mask:0xf bank_mask:0xf
	v_mov_b32_dpp v195, v187 quad_perm:[2,3,0,1] row_mask:0xf bank_mask:0xf
	v_mov_b32_dpp v196, v192 quad_perm:[2,3,0,1] row_mask:0xf bank_mask:0xf
	v_cndmask_b32_e64 v108, v108, v193, vcc
	v_cndmask_b32_e64 v110, v193, v110, vcc
	v_cndmask_b32_e64 v109, v109, v194, vcc
	v_cndmask_b32_e64 v111, v194, v111, vcc
	v_cndmask_b32_e64 v104, v104, v195, vcc
	v_cndmask_b32_e64 v106, v195, v106, vcc
	v_cndmask_b32_e64 v105, v105, v196, vcc
	v_cndmask_b32_e64 v107, v196, v107, vcc
	v_cvt_pk_bf16_f32 v146, v108, v109
	v_cvt_pk_bf16_f32 v147, v110, v111
	s_mov_b64 s[16:17], 0x20
	v_lshl_add_u64 v[138:139], v[132:133], 0, s[16:17]
	global_store_dwordx2 v[138:139], v[146:147], off
	v_cvt_pk_bf16_f32 v184, v104, v105
	v_cvt_pk_bf16_f32 v185, v106, v107
	s_mov_b64 s[16:17], 0x48020
	v_lshl_add_u64 v[140:141], v[132:133], 0, s[16:17]
	global_store_dwordx2 v[140:141], v[184:185], off
	v_cndmask_b32_e64 v131, v101, v100, s[40:41]
	v_cndmask_b32_e64 v186, v103, v102, s[40:41]
	v_cndmask_b32_e64 v187, v97, v96, s[40:41]
	v_cndmask_b32_e64 v192, v99, v98, s[40:41]
	v_mov_b32_dpp v193, v131 quad_perm:[1,0,3,2] row_mask:0xf bank_mask:0xf
	v_mov_b32_dpp v194, v186 quad_perm:[1,0,3,2] row_mask:0xf bank_mask:0xf
	v_mov_b32_dpp v195, v187 quad_perm:[1,0,3,2] row_mask:0xf bank_mask:0xf
	v_mov_b32_dpp v196, v192 quad_perm:[1,0,3,2] row_mask:0xf bank_mask:0xf
	v_cndmask_b32_e64 v100, v100, v193, s[40:41]
	v_cndmask_b32_e64 v101, v193, v101, s[40:41]
	v_cndmask_b32_e64 v102, v102, v194, s[40:41]
	v_cndmask_b32_e64 v103, v194, v103, s[40:41]
	v_cndmask_b32_e64 v96, v96, v195, s[40:41]
	v_cndmask_b32_e64 v97, v195, v97, s[40:41]
	v_cndmask_b32_e64 v98, v98, v196, s[40:41]
	v_cndmask_b32_e64 v99, v196, v99, s[40:41]
	v_cndmask_b32_e64 v131, v102, v100, vcc
	v_cndmask_b32_e64 v186, v103, v101, vcc
	v_cndmask_b32_e64 v187, v98, v96, vcc
	v_cndmask_b32_e64 v192, v99, v97, vcc
	v_mov_b32_dpp v193, v131 quad_perm:[2,3,0,1] row_mask:0xf bank_mask:0xf
	v_mov_b32_dpp v194, v186 quad_perm:[2,3,0,1] row_mask:0xf bank_mask:0xf
	v_mov_b32_dpp v195, v187 quad_perm:[2,3,0,1] row_mask:0xf bank_mask:0xf
	v_mov_b32_dpp v196, v192 quad_perm:[2,3,0,1] row_mask:0xf bank_mask:0xf
	v_cndmask_b32_e64 v100, v100, v193, vcc
	v_cndmask_b32_e64 v102, v193, v102, vcc
	v_cndmask_b32_e64 v101, v101, v194, vcc
	v_cndmask_b32_e64 v103, v194, v103, vcc
	v_cndmask_b32_e64 v96, v96, v195, vcc
	v_cndmask_b32_e64 v98, v195, v98, vcc
	v_cndmask_b32_e64 v97, v97, v196, vcc
	v_cndmask_b32_e64 v99, v196, v99, vcc
	v_cvt_pk_bf16_f32 v146, v100, v101
	v_cvt_pk_bf16_f32 v147, v102, v103
	s_mov_b64 s[16:17], 0x240020
	v_lshl_add_u64 v[138:139], v[132:133], 0, s[16:17]
	global_store_dwordx2 v[138:139], v[146:147], off
	v_cvt_pk_bf16_f32 v184, v96, v97
	v_cvt_pk_bf16_f32 v185, v98, v99
	s_mov_b64 s[16:17], 0x288020
	v_lshl_add_u64 v[140:141], v[132:133], 0, s[16:17]
	global_store_dwordx2 v[140:141], v[184:185], off
	s_mov_b64 s[16:17], 0x2000
	v_lshl_add_u64 v[142:143], v[136:137], 0, s[16:17]
	s_andn2_b64 s[16:17], exec, s[56:57]
	s_cmp_lg_u64 s[16:17], 0
	s_cbranch_scc1 .Lvt_noctx2
	global_store_dwordx4 v[142:143], v[92:95], off
	global_store_dwordx4 v[142:143], v[88:91], off offset:16
	global_store_dwordx4 v[142:143], v[84:87], off offset:128
	global_store_dwordx4 v[142:143], v[80:83], off offset:144
	s_nop 1
.Lvt_noctx2:
	v_cndmask_b32_e64 v131, v93, v92, s[40:41]
	v_cndmask_b32_e64 v186, v95, v94, s[40:41]
	v_cndmask_b32_e64 v187, v89, v88, s[40:41]
	v_cndmask_b32_e64 v192, v91, v90, s[40:41]
	v_mov_b32_dpp v193, v131 quad_perm:[1,0,3,2] row_mask:0xf bank_mask:0xf
	v_mov_b32_dpp v194, v186 quad_perm:[1,0,3,2] row_mask:0xf bank_mask:0xf
	v_mov_b32_dpp v195, v187 quad_perm:[1,0,3,2] row_mask:0xf bank_mask:0xf
	v_mov_b32_dpp v196, v192 quad_perm:[1,0,3,2] row_mask:0xf bank_mask:0xf
	v_cndmask_b32_e64 v92, v92, v193, s[40:41]
	v_cndmask_b32_e64 v93, v193, v93, s[40:41]
	v_cndmask_b32_e64 v94, v94, v194, s[40:41]
	v_cndmask_b32_e64 v95, v194, v95, s[40:41]
	v_cndmask_b32_e64 v88, v88, v195, s[40:41]
	v_cndmask_b32_e64 v89, v195, v89, s[40:41]
	v_cndmask_b32_e64 v90, v90, v196, s[40:41]
	v_cndmask_b32_e64 v91, v196, v91, s[40:41]
	v_cndmask_b32_e64 v131, v94, v92, vcc
	v_cndmask_b32_e64 v186, v95, v93, vcc
	v_cndmask_b32_e64 v187, v90, v88, vcc
	v_cndmask_b32_e64 v192, v91, v89, vcc
	v_mov_b32_dpp v193, v131 quad_perm:[2,3,0,1] row_mask:0xf bank_mask:0xf
	v_mov_b32_dpp v194, v186 quad_perm:[2,3,0,1] row_mask:0xf bank_mask:0xf
	v_mov_b32_dpp v195, v187 quad_perm:[2,3,0,1] row_mask:0xf bank_mask:0xf
	v_mov_b32_dpp v196, v192 quad_perm:[2,3,0,1] row_mask:0xf bank_mask:0xf
	v_cndmask_b32_e64 v92, v92, v193, vcc
	v_cndmask_b32_e64 v94, v193, v94, vcc
	v_cndmask_b32_e64 v93, v93, v194, vcc
	v_cndmask_b32_e64 v95, v194, v95, vcc
	v_cndmask_b32_e64 v88, v88, v195, vcc
	v_cndmask_b32_e64 v90, v195, v90, vcc
	v_cndmask_b32_e64 v89, v89, v196, vcc
	v_cndmask_b32_e64 v91, v196, v91, vcc
	v_cvt_pk_bf16_f32 v146, v92, v93
	v_cvt_pk_bf16_f32 v147, v94, v95
	s_mov_b64 s[16:17], 0x40
	v_lshl_add_u64 v[138:139], v[132:133], 0, s[16:17]
	global_store_dwordx2 v[138:139], v[146:147], off
	v_cvt_pk_bf16_f32 v184, v88, v89
	v_cvt_pk_bf16_f32 v185, v90, v91
	s_mov_b64 s[16:17], 0x48040
	v_lshl_add_u64 v[140:141], v[132:133], 0, s[16:17]
	global_store_dwordx2 v[140:141], v[184:185], off
	v_cndmask_b32_e64 v131, v85, v84, s[40:41]
	v_cndmask_b32_e64 v186, v87, v86, s[40:41]
	v_cndmask_b32_e64 v187, v81, v80, s[40:41]
	v_cndmask_b32_e64 v192, v83, v82, s[40:41]
	v_mov_b32_dpp v193, v131 quad_perm:[1,0,3,2] row_mask:0xf bank_mask:0xf
	v_mov_b32_dpp v194, v186 quad_perm:[1,0,3,2] row_mask:0xf bank_mask:0xf
	v_mov_b32_dpp v195, v187 quad_perm:[1,0,3,2] row_mask:0xf bank_mask:0xf
	v_mov_b32_dpp v196, v192 quad_perm:[1,0,3,2] row_mask:0xf bank_mask:0xf
	v_cndmask_b32_e64 v84, v84, v193, s[40:41]
	v_cndmask_b32_e64 v85, v193, v85, s[40:41]
	v_cndmask_b32_e64 v86, v86, v194, s[40:41]
	v_cndmask_b32_e64 v87, v194, v87, s[40:41]
	v_cndmask_b32_e64 v80, v80, v195, s[40:41]
	v_cndmask_b32_e64 v81, v195, v81, s[40:41]
	v_cndmask_b32_e64 v82, v82, v196, s[40:41]
	v_cndmask_b32_e64 v83, v196, v83, s[40:41]
	v_cndmask_b32_e64 v131, v86, v84, vcc
	v_cndmask_b32_e64 v186, v87, v85, vcc
	v_cndmask_b32_e64 v187, v82, v80, vcc
	v_cndmask_b32_e64 v192, v83, v81, vcc
	v_mov_b32_dpp v193, v131 quad_perm:[2,3,0,1] row_mask:0xf bank_mask:0xf
	v_mov_b32_dpp v194, v186 quad_perm:[2,3,0,1] row_mask:0xf bank_mask:0xf
	v_mov_b32_dpp v195, v187 quad_perm:[2,3,0,1] row_mask:0xf bank_mask:0xf
	v_mov_b32_dpp v196, v192 quad_perm:[2,3,0,1] row_mask:0xf bank_mask:0xf
	v_cndmask_b32_e64 v84, v84, v193, vcc
	v_cndmask_b32_e64 v86, v193, v86, vcc
	v_cndmask_b32_e64 v85, v85, v194, vcc
	v_cndmask_b32_e64 v87, v194, v87, vcc
	v_cndmask_b32_e64 v80, v80, v195, vcc
	v_cndmask_b32_e64 v82, v195, v82, vcc
	v_cndmask_b32_e64 v81, v81, v196, vcc
	v_cndmask_b32_e64 v83, v196, v83, vcc
	v_cvt_pk_bf16_f32 v146, v84, v85
	v_cvt_pk_bf16_f32 v147, v86, v87
	s_mov_b64 s[16:17], 0x240040
	v_lshl_add_u64 v[138:139], v[132:133], 0, s[16:17]
	global_store_dwordx2 v[138:139], v[146:147], off
	v_cvt_pk_bf16_f32 v184, v80, v81
	v_cvt_pk_bf16_f32 v185, v82, v83
	s_mov_b64 s[16:17], 0x288040
	v_lshl_add_u64 v[140:141], v[132:133], 0, s[16:17]
	global_store_dwordx2 v[140:141], v[184:185], off
	s_mov_b64 s[16:17], 0x3000
	v_lshl_add_u64 v[142:143], v[136:137], 0, s[16:17]
	s_andn2_b64 s[16:17], exec, s[56:57]
	s_cmp_lg_u64 s[16:17], 0
	s_cbranch_scc1 .Lvt_noctx3
	global_store_dwordx4 v[142:143], v[76:79], off
	global_store_dwordx4 v[142:143], v[72:75], off offset:16
	global_store_dwordx4 v[142:143], v[68:71], off offset:128
	global_store_dwordx4 v[142:143], v[64:67], off offset:144
	s_nop 1
.Lvt_noctx3:
	v_cndmask_b32_e64 v131, v77, v76, s[40:41]
	v_cndmask_b32_e64 v186, v79, v78, s[40:41]
	v_cndmask_b32_e64 v187, v73, v72, s[40:41]
	v_cndmask_b32_e64 v192, v75, v74, s[40:41]
	v_mov_b32_dpp v193, v131 quad_perm:[1,0,3,2] row_mask:0xf bank_mask:0xf
	v_mov_b32_dpp v194, v186 quad_perm:[1,0,3,2] row_mask:0xf bank_mask:0xf
	v_mov_b32_dpp v195, v187 quad_perm:[1,0,3,2] row_mask:0xf bank_mask:0xf
	v_mov_b32_dpp v196, v192 quad_perm:[1,0,3,2] row_mask:0xf bank_mask:0xf
	v_cndmask_b32_e64 v76, v76, v193, s[40:41]
	v_cndmask_b32_e64 v77, v193, v77, s[40:41]
	v_cndmask_b32_e64 v78, v78, v194, s[40:41]
	v_cndmask_b32_e64 v79, v194, v79, s[40:41]
	v_cndmask_b32_e64 v72, v72, v195, s[40:41]
	v_cndmask_b32_e64 v73, v195, v73, s[40:41]
	v_cndmask_b32_e64 v74, v74, v196, s[40:41]
	v_cndmask_b32_e64 v75, v196, v75, s[40:41]
	v_cndmask_b32_e64 v131, v78, v76, vcc
	v_cndmask_b32_e64 v186, v79, v77, vcc
	v_cndmask_b32_e64 v187, v74, v72, vcc
	v_cndmask_b32_e64 v192, v75, v73, vcc
	v_mov_b32_dpp v193, v131 quad_perm:[2,3,0,1] row_mask:0xf bank_mask:0xf
	v_mov_b32_dpp v194, v186 quad_perm:[2,3,0,1] row_mask:0xf bank_mask:0xf
	v_mov_b32_dpp v195, v187 quad_perm:[2,3,0,1] row_mask:0xf bank_mask:0xf
	v_mov_b32_dpp v196, v192 quad_perm:[2,3,0,1] row_mask:0xf bank_mask:0xf
	v_cndmask_b32_e64 v76, v76, v193, vcc
	v_cndmask_b32_e64 v78, v193, v78, vcc
	v_cndmask_b32_e64 v77, v77, v194, vcc
	v_cndmask_b32_e64 v79, v194, v79, vcc
	v_cndmask_b32_e64 v72, v72, v195, vcc
	v_cndmask_b32_e64 v74, v195, v74, vcc
	v_cndmask_b32_e64 v73, v73, v196, vcc
	v_cndmask_b32_e64 v75, v196, v75, vcc
	v_cvt_pk_bf16_f32 v146, v76, v77
	v_cvt_pk_bf16_f32 v147, v78, v79
	s_mov_b64 s[16:17], 0x60
	v_lshl_add_u64 v[138:139], v[132:133], 0, s[16:17]
	global_store_dwordx2 v[138:139], v[146:147], off
	v_cvt_pk_bf16_f32 v184, v72, v73
	v_cvt_pk_bf16_f32 v185, v74, v75
	s_mov_b64 s[16:17], 0x48060
	v_lshl_add_u64 v[140:141], v[132:133], 0, s[16:17]
	global_store_dwordx2 v[140:141], v[184:185], off
	v_cndmask_b32_e64 v131, v69, v68, s[40:41]
	v_cndmask_b32_e64 v186, v71, v70, s[40:41]
	v_cndmask_b32_e64 v187, v65, v64, s[40:41]
	v_cndmask_b32_e64 v192, v67, v66, s[40:41]
	v_mov_b32_dpp v193, v131 quad_perm:[1,0,3,2] row_mask:0xf bank_mask:0xf
	v_mov_b32_dpp v194, v186 quad_perm:[1,0,3,2] row_mask:0xf bank_mask:0xf
	v_mov_b32_dpp v195, v187 quad_perm:[1,0,3,2] row_mask:0xf bank_mask:0xf
	v_mov_b32_dpp v196, v192 quad_perm:[1,0,3,2] row_mask:0xf bank_mask:0xf
	v_cndmask_b32_e64 v68, v68, v193, s[40:41]
	v_cndmask_b32_e64 v69, v193, v69, s[40:41]
	v_cndmask_b32_e64 v70, v70, v194, s[40:41]
	v_cndmask_b32_e64 v71, v194, v71, s[40:41]
	v_cndmask_b32_e64 v64, v64, v195, s[40:41]
	v_cndmask_b32_e64 v65, v195, v65, s[40:41]
	v_cndmask_b32_e64 v66, v66, v196, s[40:41]
	v_cndmask_b32_e64 v67, v196, v67, s[40:41]
	v_cndmask_b32_e64 v131, v70, v68, vcc
	v_cndmask_b32_e64 v186, v71, v69, vcc
	v_cndmask_b32_e64 v187, v66, v64, vcc
	v_cndmask_b32_e64 v192, v67, v65, vcc
	v_mov_b32_dpp v193, v131 quad_perm:[2,3,0,1] row_mask:0xf bank_mask:0xf
	v_mov_b32_dpp v194, v186 quad_perm:[2,3,0,1] row_mask:0xf bank_mask:0xf
	v_mov_b32_dpp v195, v187 quad_perm:[2,3,0,1] row_mask:0xf bank_mask:0xf
	v_mov_b32_dpp v196, v192 quad_perm:[2,3,0,1] row_mask:0xf bank_mask:0xf
	v_cndmask_b32_e64 v68, v68, v193, vcc
	v_cndmask_b32_e64 v70, v193, v70, vcc
	v_cndmask_b32_e64 v69, v69, v194, vcc
	v_cndmask_b32_e64 v71, v194, v71, vcc
	v_cndmask_b32_e64 v64, v64, v195, vcc
	v_cndmask_b32_e64 v66, v195, v66, vcc
	v_cndmask_b32_e64 v65, v65, v196, vcc
	v_cndmask_b32_e64 v67, v196, v67, vcc
	v_cvt_pk_bf16_f32 v146, v68, v69
	v_cvt_pk_bf16_f32 v147, v70, v71
	s_mov_b64 s[16:17], 0x240060
	v_lshl_add_u64 v[138:139], v[132:133], 0, s[16:17]
	global_store_dwordx2 v[138:139], v[146:147], off
	v_cvt_pk_bf16_f32 v184, v64, v65
	v_cvt_pk_bf16_f32 v185, v66, v67
	s_mov_b64 s[16:17], 0x288060
	v_lshl_add_u64 v[140:141], v[132:133], 0, s[16:17]
	global_store_dwordx2 v[140:141], v[184:185], off
	s_mov_b64 s[16:17], 0x8000
	v_lshl_add_u64 v[142:143], v[136:137], 0, s[16:17]
	s_andn2_b64 s[16:17], exec, s[56:57]
	s_cmp_lg_u64 s[16:17], 0
	s_cbranch_scc1 .Lvt_noctx4
	global_store_dwordx4 v[142:143], v[60:63], off
	global_store_dwordx4 v[142:143], v[56:59], off offset:16
	global_store_dwordx4 v[142:143], v[52:55], off offset:128
	global_store_dwordx4 v[142:143], v[48:51], off offset:144
	s_nop 1
.Lvt_noctx4:
	v_cndmask_b32_e64 v131, v61, v60, s[40:41]
	v_cndmask_b32_e64 v186, v63, v62, s[40:41]
	v_cndmask_b32_e64 v187, v57, v56, s[40:41]
	v_cndmask_b32_e64 v192, v59, v58, s[40:41]
	v_mov_b32_dpp v193, v131 quad_perm:[1,0,3,2] row_mask:0xf bank_mask:0xf
	v_mov_b32_dpp v194, v186 quad_perm:[1,0,3,2] row_mask:0xf bank_mask:0xf
	v_mov_b32_dpp v195, v187 quad_perm:[1,0,3,2] row_mask:0xf bank_mask:0xf
	v_mov_b32_dpp v196, v192 quad_perm:[1,0,3,2] row_mask:0xf bank_mask:0xf
	v_cndmask_b32_e64 v60, v60, v193, s[40:41]
	v_cndmask_b32_e64 v61, v193, v61, s[40:41]
	v_cndmask_b32_e64 v62, v62, v194, s[40:41]
	v_cndmask_b32_e64 v63, v194, v63, s[40:41]
	v_cndmask_b32_e64 v56, v56, v195, s[40:41]
	v_cndmask_b32_e64 v57, v195, v57, s[40:41]
	v_cndmask_b32_e64 v58, v58, v196, s[40:41]
	v_cndmask_b32_e64 v59, v196, v59, s[40:41]
	v_cndmask_b32_e64 v131, v62, v60, vcc
	v_cndmask_b32_e64 v186, v63, v61, vcc
	v_cndmask_b32_e64 v187, v58, v56, vcc
	v_cndmask_b32_e64 v192, v59, v57, vcc
	v_mov_b32_dpp v193, v131 quad_perm:[2,3,0,1] row_mask:0xf bank_mask:0xf
	v_mov_b32_dpp v194, v186 quad_perm:[2,3,0,1] row_mask:0xf bank_mask:0xf
	v_mov_b32_dpp v195, v187 quad_perm:[2,3,0,1] row_mask:0xf bank_mask:0xf
	v_mov_b32_dpp v196, v192 quad_perm:[2,3,0,1] row_mask:0xf bank_mask:0xf
	v_cndmask_b32_e64 v60, v60, v193, vcc
	v_cndmask_b32_e64 v62, v193, v62, vcc
	v_cndmask_b32_e64 v61, v61, v194, vcc
	v_cndmask_b32_e64 v63, v194, v63, vcc
	v_cndmask_b32_e64 v56, v56, v195, vcc
	v_cndmask_b32_e64 v58, v195, v58, vcc
	v_cndmask_b32_e64 v57, v57, v196, vcc
	v_cndmask_b32_e64 v59, v196, v59, vcc
	v_cvt_pk_bf16_f32 v146, v60, v61
	v_cvt_pk_bf16_f32 v147, v62, v63
	s_mov_b64 s[16:17], 0x100
	v_lshl_add_u64 v[138:139], v[132:133], 0, s[16:17]
	global_store_dwordx2 v[138:139], v[146:147], off
	v_cvt_pk_bf16_f32 v184, v56, v57
	v_cvt_pk_bf16_f32 v185, v58, v59
	s_mov_b64 s[16:17], 0x48100
	v_lshl_add_u64 v[140:141], v[132:133], 0, s[16:17]
	global_store_dwordx2 v[140:141], v[184:185], off
	v_cndmask_b32_e64 v131, v53, v52, s[40:41]
	v_cndmask_b32_e64 v186, v55, v54, s[40:41]
	v_cndmask_b32_e64 v187, v49, v48, s[40:41]
	v_cndmask_b32_e64 v192, v51, v50, s[40:41]
	v_mov_b32_dpp v193, v131 quad_perm:[1,0,3,2] row_mask:0xf bank_mask:0xf
	v_mov_b32_dpp v194, v186 quad_perm:[1,0,3,2] row_mask:0xf bank_mask:0xf
	v_mov_b32_dpp v195, v187 quad_perm:[1,0,3,2] row_mask:0xf bank_mask:0xf
	v_mov_b32_dpp v196, v192 quad_perm:[1,0,3,2] row_mask:0xf bank_mask:0xf
	v_cndmask_b32_e64 v52, v52, v193, s[40:41]
	v_cndmask_b32_e64 v53, v193, v53, s[40:41]
	v_cndmask_b32_e64 v54, v54, v194, s[40:41]
	v_cndmask_b32_e64 v55, v194, v55, s[40:41]
	v_cndmask_b32_e64 v48, v48, v195, s[40:41]
	v_cndmask_b32_e64 v49, v195, v49, s[40:41]
	v_cndmask_b32_e64 v50, v50, v196, s[40:41]
	v_cndmask_b32_e64 v51, v196, v51, s[40:41]
	v_cndmask_b32_e64 v131, v54, v52, vcc
	v_cndmask_b32_e64 v186, v55, v53, vcc
	v_cndmask_b32_e64 v187, v50, v48, vcc
	v_cndmask_b32_e64 v192, v51, v49, vcc
	v_mov_b32_dpp v193, v131 quad_perm:[2,3,0,1] row_mask:0xf bank_mask:0xf
	v_mov_b32_dpp v194, v186 quad_perm:[2,3,0,1] row_mask:0xf bank_mask:0xf
	v_mov_b32_dpp v195, v187 quad_perm:[2,3,0,1] row_mask:0xf bank_mask:0xf
	v_mov_b32_dpp v196, v192 quad_perm:[2,3,0,1] row_mask:0xf bank_mask:0xf
	v_cndmask_b32_e64 v52, v52, v193, vcc
	v_cndmask_b32_e64 v54, v193, v54, vcc
	v_cndmask_b32_e64 v53, v53, v194, vcc
	v_cndmask_b32_e64 v55, v194, v55, vcc
	v_cndmask_b32_e64 v48, v48, v195, vcc
	v_cndmask_b32_e64 v50, v195, v50, vcc
	v_cndmask_b32_e64 v49, v49, v196, vcc
	v_cndmask_b32_e64 v51, v196, v51, vcc
	v_cvt_pk_bf16_f32 v146, v52, v53
	v_cvt_pk_bf16_f32 v147, v54, v55
	s_mov_b64 s[16:17], 0x240100
	v_lshl_add_u64 v[138:139], v[132:133], 0, s[16:17]
	global_store_dwordx2 v[138:139], v[146:147], off
	v_cvt_pk_bf16_f32 v184, v48, v49
	v_cvt_pk_bf16_f32 v185, v50, v51
	s_mov_b64 s[16:17], 0x288100
	v_lshl_add_u64 v[140:141], v[132:133], 0, s[16:17]
	global_store_dwordx2 v[140:141], v[184:185], off
	s_mov_b64 s[16:17], 0x9000
	v_lshl_add_u64 v[142:143], v[136:137], 0, s[16:17]
	s_andn2_b64 s[16:17], exec, s[56:57]
	s_cmp_lg_u64 s[16:17], 0
	s_cbranch_scc1 .Lvt_noctx5
	global_store_dwordx4 v[142:143], v[44:47], off
	global_store_dwordx4 v[142:143], v[40:43], off offset:16
	global_store_dwordx4 v[142:143], v[36:39], off offset:128
	global_store_dwordx4 v[142:143], v[32:35], off offset:144
	s_nop 1
.Lvt_noctx5:
	v_cndmask_b32_e64 v131, v45, v44, s[40:41]
	v_cndmask_b32_e64 v186, v47, v46, s[40:41]
	v_cndmask_b32_e64 v187, v41, v40, s[40:41]
	v_cndmask_b32_e64 v192, v43, v42, s[40:41]
	v_mov_b32_dpp v193, v131 quad_perm:[1,0,3,2] row_mask:0xf bank_mask:0xf
	v_mov_b32_dpp v194, v186 quad_perm:[1,0,3,2] row_mask:0xf bank_mask:0xf
	v_mov_b32_dpp v195, v187 quad_perm:[1,0,3,2] row_mask:0xf bank_mask:0xf
	v_mov_b32_dpp v196, v192 quad_perm:[1,0,3,2] row_mask:0xf bank_mask:0xf
	v_cndmask_b32_e64 v44, v44, v193, s[40:41]
	v_cndmask_b32_e64 v45, v193, v45, s[40:41]
	v_cndmask_b32_e64 v46, v46, v194, s[40:41]
	v_cndmask_b32_e64 v47, v194, v47, s[40:41]
	v_cndmask_b32_e64 v40, v40, v195, s[40:41]
	v_cndmask_b32_e64 v41, v195, v41, s[40:41]
	v_cndmask_b32_e64 v42, v42, v196, s[40:41]
	v_cndmask_b32_e64 v43, v196, v43, s[40:41]
	v_cndmask_b32_e64 v131, v46, v44, vcc
	v_cndmask_b32_e64 v186, v47, v45, vcc
	v_cndmask_b32_e64 v187, v42, v40, vcc
	v_cndmask_b32_e64 v192, v43, v41, vcc
	v_mov_b32_dpp v193, v131 quad_perm:[2,3,0,1] row_mask:0xf bank_mask:0xf
	v_mov_b32_dpp v194, v186 quad_perm:[2,3,0,1] row_mask:0xf bank_mask:0xf
	v_mov_b32_dpp v195, v187 quad_perm:[2,3,0,1] row_mask:0xf bank_mask:0xf
	v_mov_b32_dpp v196, v192 quad_perm:[2,3,0,1] row_mask:0xf bank_mask:0xf
	v_cndmask_b32_e64 v44, v44, v193, vcc
	v_cndmask_b32_e64 v46, v193, v46, vcc
	v_cndmask_b32_e64 v45, v45, v194, vcc
	v_cndmask_b32_e64 v47, v194, v47, vcc
	v_cndmask_b32_e64 v40, v40, v195, vcc
	v_cndmask_b32_e64 v42, v195, v42, vcc
	v_cndmask_b32_e64 v41, v41, v196, vcc
	v_cndmask_b32_e64 v43, v196, v43, vcc
	v_cvt_pk_bf16_f32 v146, v44, v45
	v_cvt_pk_bf16_f32 v147, v46, v47
	s_mov_b64 s[16:17], 0x120
	v_lshl_add_u64 v[138:139], v[132:133], 0, s[16:17]
	global_store_dwordx2 v[138:139], v[146:147], off
	v_cvt_pk_bf16_f32 v184, v40, v41
	v_cvt_pk_bf16_f32 v185, v42, v43
	s_mov_b64 s[16:17], 0x48120
	v_lshl_add_u64 v[140:141], v[132:133], 0, s[16:17]
	global_store_dwordx2 v[140:141], v[184:185], off
	v_cndmask_b32_e64 v131, v37, v36, s[40:41]
	v_cndmask_b32_e64 v186, v39, v38, s[40:41]
	v_cndmask_b32_e64 v187, v33, v32, s[40:41]
	v_cndmask_b32_e64 v192, v35, v34, s[40:41]
	v_mov_b32_dpp v193, v131 quad_perm:[1,0,3,2] row_mask:0xf bank_mask:0xf
	v_mov_b32_dpp v194, v186 quad_perm:[1,0,3,2] row_mask:0xf bank_mask:0xf
	v_mov_b32_dpp v195, v187 quad_perm:[1,0,3,2] row_mask:0xf bank_mask:0xf
	v_mov_b32_dpp v196, v192 quad_perm:[1,0,3,2] row_mask:0xf bank_mask:0xf
	v_cndmask_b32_e64 v36, v36, v193, s[40:41]
	v_cndmask_b32_e64 v37, v193, v37, s[40:41]
	v_cndmask_b32_e64 v38, v38, v194, s[40:41]
	v_cndmask_b32_e64 v39, v194, v39, s[40:41]
	v_cndmask_b32_e64 v32, v32, v195, s[40:41]
	v_cndmask_b32_e64 v33, v195, v33, s[40:41]
	v_cndmask_b32_e64 v34, v34, v196, s[40:41]
	v_cndmask_b32_e64 v35, v196, v35, s[40:41]
	v_cndmask_b32_e64 v131, v38, v36, vcc
	v_cndmask_b32_e64 v186, v39, v37, vcc
	v_cndmask_b32_e64 v187, v34, v32, vcc
	v_cndmask_b32_e64 v192, v35, v33, vcc
	v_mov_b32_dpp v193, v131 quad_perm:[2,3,0,1] row_mask:0xf bank_mask:0xf
	v_mov_b32_dpp v194, v186 quad_perm:[2,3,0,1] row_mask:0xf bank_mask:0xf
	v_mov_b32_dpp v195, v187 quad_perm:[2,3,0,1] row_mask:0xf bank_mask:0xf
	v_mov_b32_dpp v196, v192 quad_perm:[2,3,0,1] row_mask:0xf bank_mask:0xf
	v_cndmask_b32_e64 v36, v36, v193, vcc
	v_cndmask_b32_e64 v38, v193, v38, vcc
	v_cndmask_b32_e64 v37, v37, v194, vcc
	v_cndmask_b32_e64 v39, v194, v39, vcc
	v_cndmask_b32_e64 v32, v32, v195, vcc
	v_cndmask_b32_e64 v34, v195, v34, vcc
	v_cndmask_b32_e64 v33, v33, v196, vcc
	v_cndmask_b32_e64 v35, v196, v35, vcc
	v_cvt_pk_bf16_f32 v146, v36, v37
	v_cvt_pk_bf16_f32 v147, v38, v39
	s_mov_b64 s[16:17], 0x240120
	v_lshl_add_u64 v[138:139], v[132:133], 0, s[16:17]
	global_store_dwordx2 v[138:139], v[146:147], off
	v_cvt_pk_bf16_f32 v184, v32, v33
	v_cvt_pk_bf16_f32 v185, v34, v35
	s_mov_b64 s[16:17], 0x288120
	v_lshl_add_u64 v[140:141], v[132:133], 0, s[16:17]
	global_store_dwordx2 v[140:141], v[184:185], off
	s_mov_b64 s[16:17], 0xa000
	v_lshl_add_u64 v[142:143], v[136:137], 0, s[16:17]
	s_andn2_b64 s[16:17], exec, s[56:57]
	s_cmp_lg_u64 s[16:17], 0
	s_cbranch_scc1 .Lvt_noctx6
	global_store_dwordx4 v[142:143], v[28:31], off
	global_store_dwordx4 v[142:143], v[24:27], off offset:16
	global_store_dwordx4 v[142:143], v[20:23], off offset:128
	global_store_dwordx4 v[142:143], v[16:19], off offset:144
	s_nop 1
.Lvt_noctx6:
	v_cndmask_b32_e64 v131, v29, v28, s[40:41]
	v_cndmask_b32_e64 v186, v31, v30, s[40:41]
	v_cndmask_b32_e64 v187, v25, v24, s[40:41]
	v_cndmask_b32_e64 v192, v27, v26, s[40:41]
	v_mov_b32_dpp v193, v131 quad_perm:[1,0,3,2] row_mask:0xf bank_mask:0xf
	v_mov_b32_dpp v194, v186 quad_perm:[1,0,3,2] row_mask:0xf bank_mask:0xf
	v_mov_b32_dpp v195, v187 quad_perm:[1,0,3,2] row_mask:0xf bank_mask:0xf
	v_mov_b32_dpp v196, v192 quad_perm:[1,0,3,2] row_mask:0xf bank_mask:0xf
	v_cndmask_b32_e64 v28, v28, v193, s[40:41]
	v_cndmask_b32_e64 v29, v193, v29, s[40:41]
	v_cndmask_b32_e64 v30, v30, v194, s[40:41]
	v_cndmask_b32_e64 v31, v194, v31, s[40:41]
	v_cndmask_b32_e64 v24, v24, v195, s[40:41]
	v_cndmask_b32_e64 v25, v195, v25, s[40:41]
	v_cndmask_b32_e64 v26, v26, v196, s[40:41]
	v_cndmask_b32_e64 v27, v196, v27, s[40:41]
	v_cndmask_b32_e64 v131, v30, v28, vcc
	v_cndmask_b32_e64 v186, v31, v29, vcc
	v_cndmask_b32_e64 v187, v26, v24, vcc
	v_cndmask_b32_e64 v192, v27, v25, vcc
	v_mov_b32_dpp v193, v131 quad_perm:[2,3,0,1] row_mask:0xf bank_mask:0xf
	v_mov_b32_dpp v194, v186 quad_perm:[2,3,0,1] row_mask:0xf bank_mask:0xf
	v_mov_b32_dpp v195, v187 quad_perm:[2,3,0,1] row_mask:0xf bank_mask:0xf
	v_mov_b32_dpp v196, v192 quad_perm:[2,3,0,1] row_mask:0xf bank_mask:0xf
	v_cndmask_b32_e64 v28, v28, v193, vcc
	v_cndmask_b32_e64 v30, v193, v30, vcc
	v_cndmask_b32_e64 v29, v29, v194, vcc
	v_cndmask_b32_e64 v31, v194, v31, vcc
	v_cndmask_b32_e64 v24, v24, v195, vcc
	v_cndmask_b32_e64 v26, v195, v26, vcc
	v_cndmask_b32_e64 v25, v25, v196, vcc
	v_cndmask_b32_e64 v27, v196, v27, vcc
	v_cvt_pk_bf16_f32 v146, v28, v29
	v_cvt_pk_bf16_f32 v147, v30, v31
	s_mov_b64 s[16:17], 0x140
	v_lshl_add_u64 v[138:139], v[132:133], 0, s[16:17]
	global_store_dwordx2 v[138:139], v[146:147], off
	v_cvt_pk_bf16_f32 v184, v24, v25
	v_cvt_pk_bf16_f32 v185, v26, v27
	s_mov_b64 s[16:17], 0x48140
	v_lshl_add_u64 v[140:141], v[132:133], 0, s[16:17]
	global_store_dwordx2 v[140:141], v[184:185], off
	v_cndmask_b32_e64 v131, v21, v20, s[40:41]
	v_cndmask_b32_e64 v186, v23, v22, s[40:41]
	v_cndmask_b32_e64 v187, v17, v16, s[40:41]
	v_cndmask_b32_e64 v192, v19, v18, s[40:41]
	v_mov_b32_dpp v193, v131 quad_perm:[1,0,3,2] row_mask:0xf bank_mask:0xf
	v_mov_b32_dpp v194, v186 quad_perm:[1,0,3,2] row_mask:0xf bank_mask:0xf
	v_mov_b32_dpp v195, v187 quad_perm:[1,0,3,2] row_mask:0xf bank_mask:0xf
	v_mov_b32_dpp v196, v192 quad_perm:[1,0,3,2] row_mask:0xf bank_mask:0xf
	v_cndmask_b32_e64 v20, v20, v193, s[40:41]
	v_cndmask_b32_e64 v21, v193, v21, s[40:41]
	v_cndmask_b32_e64 v22, v22, v194, s[40:41]
	v_cndmask_b32_e64 v23, v194, v23, s[40:41]
	v_cndmask_b32_e64 v16, v16, v195, s[40:41]
	v_cndmask_b32_e64 v17, v195, v17, s[40:41]
	v_cndmask_b32_e64 v18, v18, v196, s[40:41]
	v_cndmask_b32_e64 v19, v196, v19, s[40:41]
	v_cndmask_b32_e64 v131, v22, v20, vcc
	v_cndmask_b32_e64 v186, v23, v21, vcc
	v_cndmask_b32_e64 v187, v18, v16, vcc
	v_cndmask_b32_e64 v192, v19, v17, vcc
	v_mov_b32_dpp v193, v131 quad_perm:[2,3,0,1] row_mask:0xf bank_mask:0xf
	v_mov_b32_dpp v194, v186 quad_perm:[2,3,0,1] row_mask:0xf bank_mask:0xf
	v_mov_b32_dpp v195, v187 quad_perm:[2,3,0,1] row_mask:0xf bank_mask:0xf
	v_mov_b32_dpp v196, v192 quad_perm:[2,3,0,1] row_mask:0xf bank_mask:0xf
	v_cndmask_b32_e64 v20, v20, v193, vcc
	v_cndmask_b32_e64 v22, v193, v22, vcc
	v_cndmask_b32_e64 v21, v21, v194, vcc
	v_cndmask_b32_e64 v23, v194, v23, vcc
	v_cndmask_b32_e64 v16, v16, v195, vcc
	v_cndmask_b32_e64 v18, v195, v18, vcc
	v_cndmask_b32_e64 v17, v17, v196, vcc
	v_cndmask_b32_e64 v19, v196, v19, vcc
	v_cvt_pk_bf16_f32 v146, v20, v21
	v_cvt_pk_bf16_f32 v147, v22, v23
	s_mov_b64 s[16:17], 0x240140
	v_lshl_add_u64 v[138:139], v[132:133], 0, s[16:17]
	global_store_dwordx2 v[138:139], v[146:147], off
	v_cvt_pk_bf16_f32 v184, v16, v17
	v_cvt_pk_bf16_f32 v185, v18, v19
	s_mov_b64 s[16:17], 0x288140
	v_lshl_add_u64 v[140:141], v[132:133], 0, s[16:17]
	global_store_dwordx2 v[140:141], v[184:185], off
	s_mov_b64 s[16:17], 0xb000
	v_lshl_add_u64 v[142:143], v[136:137], 0, s[16:17]
	s_andn2_b64 s[16:17], exec, s[56:57]
	s_cmp_lg_u64 s[16:17], 0
	s_cbranch_scc1 .Lvt_noctx7
	global_store_dwordx4 v[142:143], v[12:15], off
	global_store_dwordx4 v[142:143], v[8:11], off offset:16
	global_store_dwordx4 v[142:143], v[4:7], off offset:128
	global_store_dwordx4 v[142:143], v[0:3], off offset:144
	s_nop 1
.Lvt_noctx7:
	v_cndmask_b32_e64 v131, v13, v12, s[40:41]
	v_cndmask_b32_e64 v186, v15, v14, s[40:41]
	v_cndmask_b32_e64 v187, v9, v8, s[40:41]
	v_cndmask_b32_e64 v192, v11, v10, s[40:41]
	v_mov_b32_dpp v193, v131 quad_perm:[1,0,3,2] row_mask:0xf bank_mask:0xf
	v_mov_b32_dpp v194, v186 quad_perm:[1,0,3,2] row_mask:0xf bank_mask:0xf
	v_mov_b32_dpp v195, v187 quad_perm:[1,0,3,2] row_mask:0xf bank_mask:0xf
	v_mov_b32_dpp v196, v192 quad_perm:[1,0,3,2] row_mask:0xf bank_mask:0xf
	v_cndmask_b32_e64 v12, v12, v193, s[40:41]
	v_cndmask_b32_e64 v13, v193, v13, s[40:41]
	v_cndmask_b32_e64 v14, v14, v194, s[40:41]
	v_cndmask_b32_e64 v15, v194, v15, s[40:41]
	v_cndmask_b32_e64 v8, v8, v195, s[40:41]
	v_cndmask_b32_e64 v9, v195, v9, s[40:41]
	v_cndmask_b32_e64 v10, v10, v196, s[40:41]
	v_cndmask_b32_e64 v11, v196, v11, s[40:41]
	v_cndmask_b32_e64 v131, v14, v12, vcc
	v_cndmask_b32_e64 v186, v15, v13, vcc
	v_cndmask_b32_e64 v187, v10, v8, vcc
	v_cndmask_b32_e64 v192, v11, v9, vcc
	v_mov_b32_dpp v193, v131 quad_perm:[2,3,0,1] row_mask:0xf bank_mask:0xf
	v_mov_b32_dpp v194, v186 quad_perm:[2,3,0,1] row_mask:0xf bank_mask:0xf
	v_mov_b32_dpp v195, v187 quad_perm:[2,3,0,1] row_mask:0xf bank_mask:0xf
	v_mov_b32_dpp v196, v192 quad_perm:[2,3,0,1] row_mask:0xf bank_mask:0xf
	v_cndmask_b32_e64 v12, v12, v193, vcc
	v_cndmask_b32_e64 v14, v193, v14, vcc
	v_cndmask_b32_e64 v13, v13, v194, vcc
	v_cndmask_b32_e64 v15, v194, v15, vcc
	v_cndmask_b32_e64 v8, v8, v195, vcc
	v_cndmask_b32_e64 v10, v195, v10, vcc
	v_cndmask_b32_e64 v9, v9, v196, vcc
	v_cndmask_b32_e64 v11, v196, v11, vcc
	v_cvt_pk_bf16_f32 v146, v12, v13
	v_cvt_pk_bf16_f32 v147, v14, v15
	s_mov_b64 s[16:17], 0x160
	v_lshl_add_u64 v[138:139], v[132:133], 0, s[16:17]
	global_store_dwordx2 v[138:139], v[146:147], off
	v_cvt_pk_bf16_f32 v184, v8, v9
	v_cvt_pk_bf16_f32 v185, v10, v11
	s_mov_b64 s[16:17], 0x48160
	v_lshl_add_u64 v[140:141], v[132:133], 0, s[16:17]
	global_store_dwordx2 v[140:141], v[184:185], off
	v_cndmask_b32_e64 v131, v5, v4, s[40:41]
	v_cndmask_b32_e64 v186, v7, v6, s[40:41]
	v_cndmask_b32_e64 v187, v1, v0, s[40:41]
	v_cndmask_b32_e64 v192, v3, v2, s[40:41]
	v_mov_b32_dpp v193, v131 quad_perm:[1,0,3,2] row_mask:0xf bank_mask:0xf
	v_mov_b32_dpp v194, v186 quad_perm:[1,0,3,2] row_mask:0xf bank_mask:0xf
	v_mov_b32_dpp v195, v187 quad_perm:[1,0,3,2] row_mask:0xf bank_mask:0xf
	v_mov_b32_dpp v196, v192 quad_perm:[1,0,3,2] row_mask:0xf bank_mask:0xf
	v_cndmask_b32_e64 v4, v4, v193, s[40:41]
	v_cndmask_b32_e64 v5, v193, v5, s[40:41]
	v_cndmask_b32_e64 v6, v6, v194, s[40:41]
	v_cndmask_b32_e64 v7, v194, v7, s[40:41]
	v_cndmask_b32_e64 v0, v0, v195, s[40:41]
	v_cndmask_b32_e64 v1, v195, v1, s[40:41]
	v_cndmask_b32_e64 v2, v2, v196, s[40:41]
	v_cndmask_b32_e64 v3, v196, v3, s[40:41]
	v_cndmask_b32_e64 v131, v6, v4, vcc
	v_cndmask_b32_e64 v186, v7, v5, vcc
	v_cndmask_b32_e64 v187, v2, v0, vcc
	v_cndmask_b32_e64 v192, v3, v1, vcc
	v_mov_b32_dpp v193, v131 quad_perm:[2,3,0,1] row_mask:0xf bank_mask:0xf
	v_mov_b32_dpp v194, v186 quad_perm:[2,3,0,1] row_mask:0xf bank_mask:0xf
	v_mov_b32_dpp v195, v187 quad_perm:[2,3,0,1] row_mask:0xf bank_mask:0xf
	v_mov_b32_dpp v196, v192 quad_perm:[2,3,0,1] row_mask:0xf bank_mask:0xf
	v_cndmask_b32_e64 v4, v4, v193, vcc
	v_cndmask_b32_e64 v6, v193, v6, vcc
	v_cndmask_b32_e64 v5, v5, v194, vcc
	v_cndmask_b32_e64 v7, v194, v7, vcc
	v_cndmask_b32_e64 v0, v0, v195, vcc
	v_cndmask_b32_e64 v2, v195, v2, vcc
	v_cndmask_b32_e64 v1, v1, v196, vcc
	v_cndmask_b32_e64 v3, v196, v3, vcc
	v_cvt_pk_bf16_f32 v146, v4, v5
	v_cvt_pk_bf16_f32 v147, v6, v7
	s_mov_b64 s[16:17], 0x240160
	v_lshl_add_u64 v[138:139], v[132:133], 0, s[16:17]
	global_store_dwordx2 v[138:139], v[146:147], off
	v_cvt_pk_bf16_f32 v184, v0, v1
	v_cvt_pk_bf16_f32 v185, v2, v3
	s_mov_b64 s[16:17], 0x288160
	v_lshl_add_u64 v[140:141], v[132:133], 0, s[16:17]
	global_store_dwordx2 v[140:141], v[184:185], off
